# K-loop: removed the back-to-back s_setprio 0 / s_setprio 1 pair between the two 16-MFMA groups of each phase (priority stays raised across all 32 MFMAs)
# baseline (speedup 1.0000x reference)
.Lno_restore:
	s_add_u32 s0, s90, 0x80
	s_addc_u32 s1, s91, 0
	s_add_u32 s11, s2, 0x100
	s_addc_u32 s24, s3, 0
	s_mov_b32 s2, 0
	s_add_i32 s90, s2, 2
	s_add_u32 s82, s0, 0x80
	s_addc_u32 s3, s1, 0
	s_add_i32 s83, 0, 0x10000
	s_cmp_eq_u32 s62, s2
	s_cselect_b32 s3, s23, s3
	s_cselect_b32 s2, s22, s82
	s_cselect_b32 vcc_hi, s13, s24
	s_cselect_b32 vcc_lo, s12, s11
	s_add_i32 s82, 0, 0x14000
	v_add_u32_e32 v140, s83, v157
	v_add_u32_e32 v144, s82, v157
	ds_read_b128 v[128:131], v140
	ds_read_b128 v[132:135], v140 offset:1024
	ds_read_b128 v[136:139], v140 offset:2048
	ds_read_b128 v[140:143], v140 offset:3072
	ds_read_b128 v[166:169], v144
	ds_read_b128 v[176:179], v144 offset:1024
	ds_read_b128 v[180:183], v144 offset:2048
	ds_read_b128 v[184:187], v144 offset:3072
	v_lshl_add_u64 v[170:171], s[0:1], 0, v[160:161]
	s_add_i32 m0, s37, 0xc000
	ds_read_b128 v[188:191], v242
	ds_read_b128 v[192:195], v242 offset:1024
	ds_read_b128 v[196:199], v242 offset:2048
	ds_read_b128 v[200:203], v242 offset:3072
	ds_read_b128 v[204:207], v242 offset:4096
	ds_read_b128 v[208:211], v242 offset:5120
	ds_read_b128 v[212:215], v242 offset:6144
	ds_read_b128 v[216:219], v242 offset:7168
	global_load_lds_dwordx4 v[170:171], off
	v_lshl_add_u64 v[170:171], s[0:1], 0, v[162:163]
	s_add_i32 m0, s37, 0xe000
	s_nop 0
	global_load_lds_dwordx4 v[170:171], off
	s_waitcnt vmcnt(8) lgkmcnt(0)
	s_barrier
	s_setprio 1
	v_mfma_f32_16x16x32_bf16 v[124:127], v[128:131], v[188:191], 0
	v_mfma_f32_16x16x32_bf16 v[120:123], v[136:139], v[188:191], 0
	v_mfma_f32_16x16x32_bf16 v[108:111], v[128:131], v[196:199], 0
	v_mfma_f32_16x16x32_bf16 v[104:107], v[136:139], v[196:199], 0
	v_mfma_f32_16x16x32_bf16 v[92:95], v[128:131], v[204:207], 0
	v_mfma_f32_16x16x32_bf16 v[88:91], v[136:139], v[204:207], 0
	v_mfma_f32_16x16x32_bf16 v[76:79], v[128:131], v[212:215], 0
	v_mfma_f32_16x16x32_bf16 v[72:75], v[136:139], v[212:215], 0
	v_mfma_f32_16x16x32_bf16 v[124:127], v[132:135], v[192:195], v[124:127]
	v_mfma_f32_16x16x32_bf16 v[120:123], v[140:143], v[192:195], v[120:123]
	v_mfma_f32_16x16x32_bf16 v[108:111], v[132:135], v[200:203], v[108:111]
	v_mfma_f32_16x16x32_bf16 v[104:107], v[140:143], v[200:203], v[104:107]
	v_mfma_f32_16x16x32_bf16 v[92:95], v[132:135], v[208:211], v[92:95]
	v_mfma_f32_16x16x32_bf16 v[88:91], v[140:143], v[208:211], v[88:91]
	v_mfma_f32_16x16x32_bf16 v[76:79], v[132:135], v[216:219], v[76:79]
	v_mfma_f32_16x16x32_bf16 v[72:75], v[140:143], v[216:219], v[72:75]
	v_mfma_f32_16x16x32_bf16 v[116:119], v[166:169], v[188:191], 0
	v_mfma_f32_16x16x32_bf16 v[112:115], v[180:183], v[188:191], 0
	v_mfma_f32_16x16x32_bf16 v[100:103], v[166:169], v[196:199], 0
	v_mfma_f32_16x16x32_bf16 v[96:99], v[180:183], v[196:199], 0
	v_mfma_f32_16x16x32_bf16 v[84:87], v[166:169], v[204:207], 0
	v_mfma_f32_16x16x32_bf16 v[80:83], v[180:183], v[204:207], 0
	v_mfma_f32_16x16x32_bf16 v[68:71], v[166:169], v[212:215], 0
	v_mfma_f32_16x16x32_bf16 v[64:67], v[180:183], v[212:215], 0
	v_mfma_f32_16x16x32_bf16 v[116:119], v[176:179], v[192:195], v[116:119]
	v_mfma_f32_16x16x32_bf16 v[112:115], v[184:187], v[192:195], v[112:115]
	v_mfma_f32_16x16x32_bf16 v[100:103], v[176:179], v[200:203], v[100:103]
	v_mfma_f32_16x16x32_bf16 v[96:99], v[184:187], v[200:203], v[96:99]
	v_mfma_f32_16x16x32_bf16 v[84:87], v[176:179], v[208:211], v[84:87]
	v_mfma_f32_16x16x32_bf16 v[80:83], v[184:187], v[208:211], v[80:83]
	v_mfma_f32_16x16x32_bf16 v[68:71], v[176:179], v[216:219], v[68:71]
	v_mfma_f32_16x16x32_bf16 v[64:67], v[184:187], v[216:219], v[64:67]
	s_setprio 0
	s_barrier
	s_add_i32 s83, s83, s36
	v_lshl_add_u64 v[170:171], vcc, 0, v[150:151]
	s_mov_b32 m0, s83
	ds_read_b128 v[188:191], v242 offset:16384
	ds_read_b128 v[192:195], v242 offset:17408
	ds_read_b128 v[196:199], v242 offset:18432
	ds_read_b128 v[200:203], v242 offset:19456
	ds_read_b128 v[204:207], v242 offset:20480
	ds_read_b128 v[208:211], v242 offset:21504
	ds_read_b128 v[212:215], v242 offset:22528
	ds_read_b128 v[216:219], v242 offset:23552
	global_load_lds_dwordx4 v[170:171], off
	s_add_i32 m0, s83, 0x2000
	v_lshl_add_u64 v[232:233], vcc, 0, v[154:155]
	s_add_u32 vcc_lo, vcc_lo, s26
	s_addc_u32 vcc_hi, vcc_hi, 0
	s_add_i32 s82, s82, s36
	global_load_lds_dwordx4 v[232:233], off
	v_lshl_add_u64 v[234:235], vcc, 0, v[150:151]
	s_mov_b32 m0, s82
	v_lshl_add_u64 v[246:247], vcc, 0, v[154:155]
	global_load_lds_dwordx4 v[234:235], off
	s_add_i32 m0, s82, 0x2000
	v_lshl_add_u64 v[248:249], s[2:3], 0, v[148:149]
	global_load_lds_dwordx4 v[246:247], off
	s_mov_b32 m0, s37
	v_lshl_add_u64 v[250:251], s[2:3], 0, v[152:153]
	global_load_lds_dwordx4 v[248:249], off
	s_mov_b32 m0, s42
	s_nop 0
	global_load_lds_dwordx4 v[250:251], off
	s_waitcnt vmcnt(8) lgkmcnt(0)
	s_barrier
	s_setprio 1
	v_mfma_f32_16x16x32_bf16 v[60:63], v[128:131], v[188:191], 0
	v_mfma_f32_16x16x32_bf16 v[56:59], v[136:139], v[188:191], 0
	v_mfma_f32_16x16x32_bf16 v[44:47], v[128:131], v[196:199], 0
	v_mfma_f32_16x16x32_bf16 v[40:43], v[136:139], v[196:199], 0
	v_mfma_f32_16x16x32_bf16 v[28:31], v[128:131], v[204:207], 0
	v_mfma_f32_16x16x32_bf16 v[24:27], v[136:139], v[204:207], 0
	v_mfma_f32_16x16x32_bf16 v[12:15], v[128:131], v[212:215], 0
	v_mfma_f32_16x16x32_bf16 v[8:11], v[136:139], v[212:215], 0
	v_mfma_f32_16x16x32_bf16 v[60:63], v[132:135], v[192:195], v[60:63]
	v_mfma_f32_16x16x32_bf16 v[56:59], v[140:143], v[192:195], v[56:59]
	v_mfma_f32_16x16x32_bf16 v[44:47], v[132:135], v[200:203], v[44:47]
	v_mfma_f32_16x16x32_bf16 v[40:43], v[140:143], v[200:203], v[40:43]
	v_mfma_f32_16x16x32_bf16 v[28:31], v[132:135], v[208:211], v[28:31]
	v_mfma_f32_16x16x32_bf16 v[24:27], v[140:143], v[208:211], v[24:27]
	v_mfma_f32_16x16x32_bf16 v[12:15], v[132:135], v[216:219], v[12:15]
	v_mfma_f32_16x16x32_bf16 v[8:11], v[140:143], v[216:219], v[8:11]
	v_mfma_f32_16x16x32_bf16 v[52:55], v[166:169], v[188:191], 0
	v_mfma_f32_16x16x32_bf16 v[48:51], v[180:183], v[188:191], 0
	v_mfma_f32_16x16x32_bf16 v[36:39], v[166:169], v[196:199], 0
	v_mfma_f32_16x16x32_bf16 v[32:35], v[180:183], v[196:199], 0
	v_mfma_f32_16x16x32_bf16 v[20:23], v[166:169], v[204:207], 0
	v_mfma_f32_16x16x32_bf16 v[16:19], v[180:183], v[204:207], 0
	v_mfma_f32_16x16x32_bf16 v[4:7], v[166:169], v[212:215], 0
	v_mfma_f32_16x16x32_bf16 v[0:3], v[180:183], v[212:215], 0
	v_mfma_f32_16x16x32_bf16 v[52:55], v[176:179], v[192:195], v[52:55]
	v_mfma_f32_16x16x32_bf16 v[48:51], v[184:187], v[192:195], v[48:51]
	v_mfma_f32_16x16x32_bf16 v[36:39], v[176:179], v[200:203], v[36:39]
	v_mfma_f32_16x16x32_bf16 v[32:35], v[184:187], v[200:203], v[32:35]
	v_mfma_f32_16x16x32_bf16 v[20:23], v[176:179], v[208:211], v[20:23]
	v_mfma_f32_16x16x32_bf16 v[16:19], v[184:187], v[208:211], v[16:19]
	v_mfma_f32_16x16x32_bf16 v[4:7], v[176:179], v[216:219], v[4:7]
	v_mfma_f32_16x16x32_bf16 v[0:3], v[184:187], v[216:219], v[0:3]
	s_setprio 0
	s_barrier
	s_add_i32 s82, 0, 0x18000
	s_add_i32 s83, 0, 0x1c000
	v_add_u32_e32 v140, s82, v157
	v_add_u32_e32 v144, s83, v157
	ds_read_b128 v[128:131], v140
	ds_read_b128 v[132:135], v140 offset:1024
	ds_read_b128 v[136:139], v140 offset:2048
	ds_read_b128 v[140:143], v140 offset:3072
	ds_read_b128 v[166:169], v144
	ds_read_b128 v[176:179], v144 offset:1024
	ds_read_b128 v[180:183], v144 offset:2048
	ds_read_b128 v[184:187], v144 offset:3072
	s_add_u32 s2, s2, s58
	s_addc_u32 s3, s3, 0
	s_mov_b32 m0, s43
	v_lshl_add_u64 v[238:239], s[2:3], 0, v[148:149]
	ds_read_b128 v[188:191], v242 offset:32768
	ds_read_b128 v[192:195], v242 offset:33792
	ds_read_b128 v[196:199], v242 offset:34816
	ds_read_b128 v[200:203], v242 offset:35840
	ds_read_b128 v[204:207], v242 offset:36864
	ds_read_b128 v[208:211], v242 offset:37888
	ds_read_b128 v[212:215], v242 offset:38912
	ds_read_b128 v[216:219], v242 offset:39936
	global_load_lds_dwordx4 v[238:239], off
	v_lshl_add_u64 v[238:239], s[2:3], 0, v[152:153]
	s_mov_b32 m0, s16
	s_nop 0
	global_load_lds_dwordx4 v[238:239], off
	s_waitcnt vmcnt(8) lgkmcnt(0)
	s_barrier
	s_setprio 1
	v_mfma_f32_16x16x32_bf16 v[124:127], v[128:131], v[188:191], v[124:127]
	v_mfma_f32_16x16x32_bf16 v[120:123], v[136:139], v[188:191], v[120:123]
	v_mfma_f32_16x16x32_bf16 v[108:111], v[128:131], v[196:199], v[108:111]
	v_mfma_f32_16x16x32_bf16 v[104:107], v[136:139], v[196:199], v[104:107]
	v_mfma_f32_16x16x32_bf16 v[92:95], v[128:131], v[204:207], v[92:95]
	v_mfma_f32_16x16x32_bf16 v[88:91], v[136:139], v[204:207], v[88:91]
	v_mfma_f32_16x16x32_bf16 v[76:79], v[128:131], v[212:215], v[76:79]
	v_mfma_f32_16x16x32_bf16 v[72:75], v[136:139], v[212:215], v[72:75]
	v_mfma_f32_16x16x32_bf16 v[124:127], v[132:135], v[192:195], v[124:127]
	v_mfma_f32_16x16x32_bf16 v[120:123], v[140:143], v[192:195], v[120:123]
	v_mfma_f32_16x16x32_bf16 v[108:111], v[132:135], v[200:203], v[108:111]
	v_mfma_f32_16x16x32_bf16 v[104:107], v[140:143], v[200:203], v[104:107]
	v_mfma_f32_16x16x32_bf16 v[92:95], v[132:135], v[208:211], v[92:95]
	v_mfma_f32_16x16x32_bf16 v[88:91], v[140:143], v[208:211], v[88:91]
	v_mfma_f32_16x16x32_bf16 v[76:79], v[132:135], v[216:219], v[76:79]
	v_mfma_f32_16x16x32_bf16 v[72:75], v[140:143], v[216:219], v[72:75]
	v_mfma_f32_16x16x32_bf16 v[116:119], v[166:169], v[188:191], v[116:119]
	v_mfma_f32_16x16x32_bf16 v[112:115], v[180:183], v[188:191], v[112:115]
	v_mfma_f32_16x16x32_bf16 v[100:103], v[166:169], v[196:199], v[100:103]
	v_mfma_f32_16x16x32_bf16 v[96:99], v[180:183], v[196:199], v[96:99]
	v_mfma_f32_16x16x32_bf16 v[84:87], v[166:169], v[204:207], v[84:87]
	v_mfma_f32_16x16x32_bf16 v[80:83], v[180:183], v[204:207], v[80:83]
	v_mfma_f32_16x16x32_bf16 v[68:71], v[166:169], v[212:215], v[68:71]
	v_mfma_f32_16x16x32_bf16 v[64:67], v[180:183], v[212:215], v[64:67]
	v_mfma_f32_16x16x32_bf16 v[116:119], v[176:179], v[192:195], v[116:119]
	v_mfma_f32_16x16x32_bf16 v[112:115], v[184:187], v[192:195], v[112:115]
	v_mfma_f32_16x16x32_bf16 v[100:103], v[176:179], v[200:203], v[100:103]
	v_mfma_f32_16x16x32_bf16 v[96:99], v[184:187], v[200:203], v[96:99]
	v_mfma_f32_16x16x32_bf16 v[84:87], v[176:179], v[208:211], v[84:87]
	v_mfma_f32_16x16x32_bf16 v[80:83], v[184:187], v[208:211], v[80:83]
	v_mfma_f32_16x16x32_bf16 v[68:71], v[176:179], v[216:219], v[68:71]
	v_mfma_f32_16x16x32_bf16 v[64:67], v[184:187], v[216:219], v[64:67]
	s_setprio 0
	s_barrier
	s_add_i32 s2, s82, s36
	v_lshl_add_u64 v[170:171], v[170:171], 0, s[30:31]
	s_mov_b32 m0, s2
	ds_read_b128 v[188:191], v242 offset:49152
	ds_read_b128 v[192:195], v242 offset:50176
	ds_read_b128 v[196:199], v242 offset:51200
	ds_read_b128 v[200:203], v242 offset:52224
	ds_read_b128 v[204:207], v242 offset:53248
	ds_read_b128 v[208:211], v242 offset:54272
	ds_read_b128 v[212:215], v242 offset:55296
	ds_read_b128 v[216:219], v242 offset:56320
	global_load_lds_dwordx4 v[170:171], off
	v_lshl_add_u64 v[170:171], v[232:233], 0, s[30:31]
	s_add_i32 m0, s2, 0x2000
	s_add_i32 s2, s83, s36
	global_load_lds_dwordx4 v[170:171], off
	v_lshl_add_u64 v[170:171], v[234:235], 0, s[30:31]
	s_mov_b32 m0, s2
	s_nop 0
	global_load_lds_dwordx4 v[170:171], off
	v_lshl_add_u64 v[170:171], v[246:247], 0, s[30:31]
	s_add_i32 m0, s2, 0x2000
	s_nop 0
	global_load_lds_dwordx4 v[170:171], off
	v_lshl_add_u64 v[170:171], v[248:249], 0, s[30:31]
	s_mov_b32 m0, s63
	s_nop 0
	global_load_lds_dwordx4 v[170:171], off
	v_lshl_add_u64 v[170:171], v[250:251], 0, s[30:31]
	s_mov_b32 m0, s18
	s_nop 0
	global_load_lds_dwordx4 v[170:171], off
	s_waitcnt vmcnt(8) lgkmcnt(0)
	s_barrier
	s_setprio 1
	v_mfma_f32_16x16x32_bf16 v[60:63], v[128:131], v[188:191], v[60:63]
	v_mfma_f32_16x16x32_bf16 v[56:59], v[136:139], v[188:191], v[56:59]
	v_mfma_f32_16x16x32_bf16 v[44:47], v[128:131], v[196:199], v[44:47]
	v_mfma_f32_16x16x32_bf16 v[40:43], v[136:139], v[196:199], v[40:43]
	v_mfma_f32_16x16x32_bf16 v[28:31], v[128:131], v[204:207], v[28:31]
	v_mfma_f32_16x16x32_bf16 v[24:27], v[136:139], v[204:207], v[24:27]
	v_mfma_f32_16x16x32_bf16 v[12:15], v[128:131], v[212:215], v[12:15]
	v_mfma_f32_16x16x32_bf16 v[8:11], v[136:139], v[212:215], v[8:11]
	v_mfma_f32_16x16x32_bf16 v[60:63], v[132:135], v[192:195], v[60:63]
	v_mfma_f32_16x16x32_bf16 v[56:59], v[140:143], v[192:195], v[56:59]
	v_mfma_f32_16x16x32_bf16 v[44:47], v[132:135], v[200:203], v[44:47]
	v_mfma_f32_16x16x32_bf16 v[40:43], v[140:143], v[200:203], v[40:43]
	v_mfma_f32_16x16x32_bf16 v[28:31], v[132:135], v[208:211], v[28:31]
	v_mfma_f32_16x16x32_bf16 v[24:27], v[140:143], v[208:211], v[24:27]
	v_mfma_f32_16x16x32_bf16 v[12:15], v[132:135], v[216:219], v[12:15]
	v_mfma_f32_16x16x32_bf16 v[8:11], v[140:143], v[216:219], v[8:11]
	v_mfma_f32_16x16x32_bf16 v[52:55], v[166:169], v[188:191], v[52:55]
	v_mfma_f32_16x16x32_bf16 v[48:51], v[180:183], v[188:191], v[48:51]
	v_mfma_f32_16x16x32_bf16 v[36:39], v[166:169], v[196:199], v[36:39]
	v_mfma_f32_16x16x32_bf16 v[32:35], v[180:183], v[196:199], v[32:35]
	v_mfma_f32_16x16x32_bf16 v[20:23], v[166:169], v[204:207], v[20:23]
	v_mfma_f32_16x16x32_bf16 v[16:19], v[180:183], v[204:207], v[16:19]
	v_mfma_f32_16x16x32_bf16 v[4:7], v[166:169], v[212:215], v[4:7]
	v_mfma_f32_16x16x32_bf16 v[0:3], v[180:183], v[212:215], v[0:3]
	v_mfma_f32_16x16x32_bf16 v[52:55], v[176:179], v[192:195], v[52:55]
	v_mfma_f32_16x16x32_bf16 v[48:51], v[184:187], v[192:195], v[48:51]
	v_mfma_f32_16x16x32_bf16 v[36:39], v[176:179], v[200:203], v[36:39]
	v_mfma_f32_16x16x32_bf16 v[32:35], v[184:187], v[200:203], v[32:35]
	v_mfma_f32_16x16x32_bf16 v[20:23], v[176:179], v[208:211], v[20:23]
	v_mfma_f32_16x16x32_bf16 v[16:19], v[184:187], v[208:211], v[16:19]
	v_mfma_f32_16x16x32_bf16 v[4:7], v[176:179], v[216:219], v[4:7]
	v_mfma_f32_16x16x32_bf16 v[0:3], v[184:187], v[216:219], v[0:3]
	s_setprio 0
	s_barrier
	s_add_u32 s0, s0, 0x100
	s_addc_u32 s1, s1, 0
	s_add_u32 s11, s11, 0x100
	s_addc_u32 s24, s24, 0
	s_cmp_ge_u32 s90, s60
	s_mov_b32 s2, s90
	s_cbranch_scc1 .LBB0_297
.LBB0_295:
	s_add_i32 s90, s2, 2
	s_add_u32 s82, s0, 0x80
	s_addc_u32 s3, s1, 0
	s_add_i32 s83, 0, 0x10000
	s_cmp_eq_u32 s62, s2
	s_cselect_b32 s3, s23, s3
	s_cselect_b32 s2, s22, s82
	s_cselect_b32 vcc_hi, s13, s24
	s_cselect_b32 vcc_lo, s12, s11
	s_add_i32 s82, 0, 0x14000
	v_add_u32_e32 v140, s83, v157
	v_add_u32_e32 v144, s82, v157
	ds_read_b128 v[128:131], v140
	ds_read_b128 v[132:135], v140 offset:1024
	ds_read_b128 v[136:139], v140 offset:2048
	ds_read_b128 v[140:143], v140 offset:3072
	ds_read_b128 v[166:169], v144
	ds_read_b128 v[176:179], v144 offset:1024
	ds_read_b128 v[180:183], v144 offset:2048
	ds_read_b128 v[184:187], v144 offset:3072
	v_lshl_add_u64 v[170:171], s[0:1], 0, v[160:161]
	s_add_i32 m0, s37, 0xc000
	ds_read_b128 v[188:191], v242
	ds_read_b128 v[192:195], v242 offset:1024
	ds_read_b128 v[196:199], v242 offset:2048
	ds_read_b128 v[200:203], v242 offset:3072
	ds_read_b128 v[204:207], v242 offset:4096
	ds_read_b128 v[208:211], v242 offset:5120
	ds_read_b128 v[212:215], v242 offset:6144
	ds_read_b128 v[216:219], v242 offset:7168
	global_load_lds_dwordx4 v[170:171], off
	v_lshl_add_u64 v[170:171], s[0:1], 0, v[162:163]
	s_add_i32 m0, s37, 0xe000
	s_nop 0
	global_load_lds_dwordx4 v[170:171], off
	s_waitcnt vmcnt(8) lgkmcnt(0)
	s_barrier
	s_setprio 1
	v_mfma_f32_16x16x32_bf16 v[124:127], v[128:131], v[188:191], v[124:127]
	v_mfma_f32_16x16x32_bf16 v[120:123], v[136:139], v[188:191], v[120:123]
	v_mfma_f32_16x16x32_bf16 v[108:111], v[128:131], v[196:199], v[108:111]
	v_mfma_f32_16x16x32_bf16 v[104:107], v[136:139], v[196:199], v[104:107]
	v_mfma_f32_16x16x32_bf16 v[92:95], v[128:131], v[204:207], v[92:95]
	v_mfma_f32_16x16x32_bf16 v[88:91], v[136:139], v[204:207], v[88:91]
	v_mfma_f32_16x16x32_bf16 v[76:79], v[128:131], v[212:215], v[76:79]
	v_mfma_f32_16x16x32_bf16 v[72:75], v[136:139], v[212:215], v[72:75]
	v_mfma_f32_16x16x32_bf16 v[124:127], v[132:135], v[192:195], v[124:127]
	v_mfma_f32_16x16x32_bf16 v[120:123], v[140:143], v[192:195], v[120:123]
	v_mfma_f32_16x16x32_bf16 v[108:111], v[132:135], v[200:203], v[108:111]
	v_mfma_f32_16x16x32_bf16 v[104:107], v[140:143], v[200:203], v[104:107]
	v_mfma_f32_16x16x32_bf16 v[92:95], v[132:135], v[208:211], v[92:95]
	v_mfma_f32_16x16x32_bf16 v[88:91], v[140:143], v[208:211], v[88:91]
	v_mfma_f32_16x16x32_bf16 v[76:79], v[132:135], v[216:219], v[76:79]
	v_mfma_f32_16x16x32_bf16 v[72:75], v[140:143], v[216:219], v[72:75]
	v_mfma_f32_16x16x32_bf16 v[116:119], v[166:169], v[188:191], v[116:119]
	v_mfma_f32_16x16x32_bf16 v[112:115], v[180:183], v[188:191], v[112:115]
	v_mfma_f32_16x16x32_bf16 v[100:103], v[166:169], v[196:199], v[100:103]
	v_mfma_f32_16x16x32_bf16 v[96:99], v[180:183], v[196:199], v[96:99]
	v_mfma_f32_16x16x32_bf16 v[84:87], v[166:169], v[204:207], v[84:87]
	v_mfma_f32_16x16x32_bf16 v[80:83], v[180:183], v[204:207], v[80:83]
	v_mfma_f32_16x16x32_bf16 v[68:71], v[166:169], v[212:215], v[68:71]
	v_mfma_f32_16x16x32_bf16 v[64:67], v[180:183], v[212:215], v[64:67]
	v_mfma_f32_16x16x32_bf16 v[116:119], v[176:179], v[192:195], v[116:119]
	v_mfma_f32_16x16x32_bf16 v[112:115], v[184:187], v[192:195], v[112:115]
	v_mfma_f32_16x16x32_bf16 v[100:103], v[176:179], v[200:203], v[100:103]
	v_mfma_f32_16x16x32_bf16 v[96:99], v[184:187], v[200:203], v[96:99]
	v_mfma_f32_16x16x32_bf16 v[84:87], v[176:179], v[208:211], v[84:87]
	v_mfma_f32_16x16x32_bf16 v[80:83], v[184:187], v[208:211], v[80:83]
	v_mfma_f32_16x16x32_bf16 v[68:71], v[176:179], v[216:219], v[68:71]
	v_mfma_f32_16x16x32_bf16 v[64:67], v[184:187], v[216:219], v[64:67]
	s_setprio 0
	s_barrier
	s_add_i32 s83, s83, s36
	v_lshl_add_u64 v[170:171], vcc, 0, v[150:151]
	s_mov_b32 m0, s83
	ds_read_b128 v[188:191], v242 offset:16384
	ds_read_b128 v[192:195], v242 offset:17408
	ds_read_b128 v[196:199], v242 offset:18432
	ds_read_b128 v[200:203], v242 offset:19456
	ds_read_b128 v[204:207], v242 offset:20480
	ds_read_b128 v[208:211], v242 offset:21504
	ds_read_b128 v[212:215], v242 offset:22528
	ds_read_b128 v[216:219], v242 offset:23552
	global_load_lds_dwordx4 v[170:171], off
	s_add_i32 m0, s83, 0x2000
	v_lshl_add_u64 v[232:233], vcc, 0, v[154:155]
	s_add_u32 vcc_lo, vcc_lo, s26
	s_addc_u32 vcc_hi, vcc_hi, 0
	s_add_i32 s82, s82, s36
	global_load_lds_dwordx4 v[232:233], off
	v_lshl_add_u64 v[234:235], vcc, 0, v[150:151]
	s_mov_b32 m0, s82
	v_lshl_add_u64 v[246:247], vcc, 0, v[154:155]
	global_load_lds_dwordx4 v[234:235], off
	s_add_i32 m0, s82, 0x2000
	v_lshl_add_u64 v[248:249], s[2:3], 0, v[148:149]
	global_load_lds_dwordx4 v[246:247], off
	s_mov_b32 m0, s37
	v_lshl_add_u64 v[250:251], s[2:3], 0, v[152:153]
	global_load_lds_dwordx4 v[248:249], off
	s_mov_b32 m0, s42
	s_nop 0
	global_load_lds_dwordx4 v[250:251], off
	s_waitcnt vmcnt(8) lgkmcnt(0)
	s_barrier
	s_setprio 1
	v_mfma_f32_16x16x32_bf16 v[60:63], v[128:131], v[188:191], v[60:63]
	v_mfma_f32_16x16x32_bf16 v[56:59], v[136:139], v[188:191], v[56:59]
	v_mfma_f32_16x16x32_bf16 v[44:47], v[128:131], v[196:199], v[44:47]
	v_mfma_f32_16x16x32_bf16 v[40:43], v[136:139], v[196:199], v[40:43]
	v_mfma_f32_16x16x32_bf16 v[28:31], v[128:131], v[204:207], v[28:31]
	v_mfma_f32_16x16x32_bf16 v[24:27], v[136:139], v[204:207], v[24:27]
	v_mfma_f32_16x16x32_bf16 v[12:15], v[128:131], v[212:215], v[12:15]
	v_mfma_f32_16x16x32_bf16 v[8:11], v[136:139], v[212:215], v[8:11]
	v_mfma_f32_16x16x32_bf16 v[60:63], v[132:135], v[192:195], v[60:63]
	v_mfma_f32_16x16x32_bf16 v[56:59], v[140:143], v[192:195], v[56:59]
	v_mfma_f32_16x16x32_bf16 v[44:47], v[132:135], v[200:203], v[44:47]
	v_mfma_f32_16x16x32_bf16 v[40:43], v[140:143], v[200:203], v[40:43]
	v_mfma_f32_16x16x32_bf16 v[28:31], v[132:135], v[208:211], v[28:31]
	v_mfma_f32_16x16x32_bf16 v[24:27], v[140:143], v[208:211], v[24:27]
	v_mfma_f32_16x16x32_bf16 v[12:15], v[132:135], v[216:219], v[12:15]
	v_mfma_f32_16x16x32_bf16 v[8:11], v[140:143], v[216:219], v[8:11]
	v_mfma_f32_16x16x32_bf16 v[52:55], v[166:169], v[188:191], v[52:55]
	v_mfma_f32_16x16x32_bf16 v[48:51], v[180:183], v[188:191], v[48:51]
	v_mfma_f32_16x16x32_bf16 v[36:39], v[166:169], v[196:199], v[36:39]
	v_mfma_f32_16x16x32_bf16 v[32:35], v[180:183], v[196:199], v[32:35]
	v_mfma_f32_16x16x32_bf16 v[20:23], v[166:169], v[204:207], v[20:23]
	v_mfma_f32_16x16x32_bf16 v[16:19], v[180:183], v[204:207], v[16:19]
	v_mfma_f32_16x16x32_bf16 v[4:7], v[166:169], v[212:215], v[4:7]
	v_mfma_f32_16x16x32_bf16 v[0:3], v[180:183], v[212:215], v[0:3]
	v_mfma_f32_16x16x32_bf16 v[52:55], v[176:179], v[192:195], v[52:55]
	v_mfma_f32_16x16x32_bf16 v[48:51], v[184:187], v[192:195], v[48:51]
	v_mfma_f32_16x16x32_bf16 v[36:39], v[176:179], v[200:203], v[36:39]
	v_mfma_f32_16x16x32_bf16 v[32:35], v[184:187], v[200:203], v[32:35]
	v_mfma_f32_16x16x32_bf16 v[20:23], v[176:179], v[208:211], v[20:23]
	v_mfma_f32_16x16x32_bf16 v[16:19], v[184:187], v[208:211], v[16:19]
	v_mfma_f32_16x16x32_bf16 v[4:7], v[176:179], v[216:219], v[4:7]
	v_mfma_f32_16x16x32_bf16 v[0:3], v[184:187], v[216:219], v[0:3]
	s_setprio 0
	s_barrier
	s_add_i32 s82, 0, 0x18000
	s_add_i32 s83, 0, 0x1c000
	v_add_u32_e32 v140, s82, v157
	v_add_u32_e32 v144, s83, v157
	ds_read_b128 v[128:131], v140
	ds_read_b128 v[132:135], v140 offset:1024
	ds_read_b128 v[136:139], v140 offset:2048
	ds_read_b128 v[140:143], v140 offset:3072
	ds_read_b128 v[166:169], v144
	ds_read_b128 v[176:179], v144 offset:1024
	ds_read_b128 v[180:183], v144 offset:2048
	ds_read_b128 v[184:187], v144 offset:3072
	s_add_u32 s2, s2, s58
	s_addc_u32 s3, s3, 0
	s_mov_b32 m0, s43
	v_lshl_add_u64 v[238:239], s[2:3], 0, v[148:149]
	ds_read_b128 v[188:191], v242 offset:32768
	ds_read_b128 v[192:195], v242 offset:33792
	ds_read_b128 v[196:199], v242 offset:34816
	ds_read_b128 v[200:203], v242 offset:35840
	ds_read_b128 v[204:207], v242 offset:36864
	ds_read_b128 v[208:211], v242 offset:37888
	ds_read_b128 v[212:215], v242 offset:38912
	ds_read_b128 v[216:219], v242 offset:39936
	global_load_lds_dwordx4 v[238:239], off
	v_lshl_add_u64 v[238:239], s[2:3], 0, v[152:153]
	s_mov_b32 m0, s16
	s_nop 0
	global_load_lds_dwordx4 v[238:239], off
	s_waitcnt vmcnt(8) lgkmcnt(0)
	s_barrier
	s_setprio 1
	v_mfma_f32_16x16x32_bf16 v[124:127], v[128:131], v[188:191], v[124:127]
	v_mfma_f32_16x16x32_bf16 v[120:123], v[136:139], v[188:191], v[120:123]
	v_mfma_f32_16x16x32_bf16 v[108:111], v[128:131], v[196:199], v[108:111]
	v_mfma_f32_16x16x32_bf16 v[104:107], v[136:139], v[196:199], v[104:107]
	v_mfma_f32_16x16x32_bf16 v[92:95], v[128:131], v[204:207], v[92:95]
	v_mfma_f32_16x16x32_bf16 v[88:91], v[136:139], v[204:207], v[88:91]
	v_mfma_f32_16x16x32_bf16 v[76:79], v[128:131], v[212:215], v[76:79]
	v_mfma_f32_16x16x32_bf16 v[72:75], v[136:139], v[212:215], v[72:75]
	v_mfma_f32_16x16x32_bf16 v[124:127], v[132:135], v[192:195], v[124:127]
	v_mfma_f32_16x16x32_bf16 v[120:123], v[140:143], v[192:195], v[120:123]
	v_mfma_f32_16x16x32_bf16 v[108:111], v[132:135], v[200:203], v[108:111]
	v_mfma_f32_16x16x32_bf16 v[104:107], v[140:143], v[200:203], v[104:107]
	v_mfma_f32_16x16x32_bf16 v[92:95], v[132:135], v[208:211], v[92:95]
	v_mfma_f32_16x16x32_bf16 v[88:91], v[140:143], v[208:211], v[88:91]
	v_mfma_f32_16x16x32_bf16 v[76:79], v[132:135], v[216:219], v[76:79]
	v_mfma_f32_16x16x32_bf16 v[72:75], v[140:143], v[216:219], v[72:75]
	v_mfma_f32_16x16x32_bf16 v[116:119], v[166:169], v[188:191], v[116:119]
	v_mfma_f32_16x16x32_bf16 v[112:115], v[180:183], v[188:191], v[112:115]
	v_mfma_f32_16x16x32_bf16 v[100:103], v[166:169], v[196:199], v[100:103]
	v_mfma_f32_16x16x32_bf16 v[96:99], v[180:183], v[196:199], v[96:99]
	v_mfma_f32_16x16x32_bf16 v[84:87], v[166:169], v[204:207], v[84:87]
	v_mfma_f32_16x16x32_bf16 v[80:83], v[180:183], v[204:207], v[80:83]
	v_mfma_f32_16x16x32_bf16 v[68:71], v[166:169], v[212:215], v[68:71]
	v_mfma_f32_16x16x32_bf16 v[64:67], v[180:183], v[212:215], v[64:67]
	v_mfma_f32_16x16x32_bf16 v[116:119], v[176:179], v[192:195], v[116:119]
	v_mfma_f32_16x16x32_bf16 v[112:115], v[184:187], v[192:195], v[112:115]
	v_mfma_f32_16x16x32_bf16 v[100:103], v[176:179], v[200:203], v[100:103]
	v_mfma_f32_16x16x32_bf16 v[96:99], v[184:187], v[200:203], v[96:99]
	v_mfma_f32_16x16x32_bf16 v[84:87], v[176:179], v[208:211], v[84:87]
	v_mfma_f32_16x16x32_bf16 v[80:83], v[184:187], v[208:211], v[80:83]
	v_mfma_f32_16x16x32_bf16 v[68:71], v[176:179], v[216:219], v[68:71]
	v_mfma_f32_16x16x32_bf16 v[64:67], v[184:187], v[216:219], v[64:67]
	s_setprio 0
	s_barrier
	s_add_i32 s2, s82, s36
	v_lshl_add_u64 v[170:171], v[170:171], 0, s[30:31]
	s_mov_b32 m0, s2
	ds_read_b128 v[188:191], v242 offset:49152
	ds_read_b128 v[192:195], v242 offset:50176
	ds_read_b128 v[196:199], v242 offset:51200
	ds_read_b128 v[200:203], v242 offset:52224
	ds_read_b128 v[204:207], v242 offset:53248
	ds_read_b128 v[208:211], v242 offset:54272
	ds_read_b128 v[212:215], v242 offset:55296
	ds_read_b128 v[216:219], v242 offset:56320
	global_load_lds_dwordx4 v[170:171], off
	v_lshl_add_u64 v[170:171], v[232:233], 0, s[30:31]
	s_add_i32 m0, s2, 0x2000
	s_add_i32 s2, s83, s36
	global_load_lds_dwordx4 v[170:171], off
	v_lshl_add_u64 v[170:171], v[234:235], 0, s[30:31]
	s_mov_b32 m0, s2
	s_nop 0
	global_load_lds_dwordx4 v[170:171], off
	v_lshl_add_u64 v[170:171], v[246:247], 0, s[30:31]
	s_add_i32 m0, s2, 0x2000
	s_nop 0
	global_load_lds_dwordx4 v[170:171], off
	v_lshl_add_u64 v[170:171], v[248:249], 0, s[30:31]
	s_mov_b32 m0, s63
	s_nop 0
	global_load_lds_dwordx4 v[170:171], off
	v_lshl_add_u64 v[170:171], v[250:251], 0, s[30:31]
	s_mov_b32 m0, s18
	s_nop 0
	global_load_lds_dwordx4 v[170:171], off
	s_waitcnt vmcnt(8) lgkmcnt(0)
	s_barrier
	s_setprio 1
	v_mfma_f32_16x16x32_bf16 v[60:63], v[128:131], v[188:191], v[60:63]
	v_mfma_f32_16x16x32_bf16 v[56:59], v[136:139], v[188:191], v[56:59]
	v_mfma_f32_16x16x32_bf16 v[44:47], v[128:131], v[196:199], v[44:47]
	v_mfma_f32_16x16x32_bf16 v[40:43], v[136:139], v[196:199], v[40:43]
	v_mfma_f32_16x16x32_bf16 v[28:31], v[128:131], v[204:207], v[28:31]
	v_mfma_f32_16x16x32_bf16 v[24:27], v[136:139], v[204:207], v[24:27]
	v_mfma_f32_16x16x32_bf16 v[12:15], v[128:131], v[212:215], v[12:15]
	v_mfma_f32_16x16x32_bf16 v[8:11], v[136:139], v[212:215], v[8:11]
	v_mfma_f32_16x16x32_bf16 v[60:63], v[132:135], v[192:195], v[60:63]
	v_mfma_f32_16x16x32_bf16 v[56:59], v[140:143], v[192:195], v[56:59]
	v_mfma_f32_16x16x32_bf16 v[44:47], v[132:135], v[200:203], v[44:47]
	v_mfma_f32_16x16x32_bf16 v[40:43], v[140:143], v[200:203], v[40:43]
	v_mfma_f32_16x16x32_bf16 v[28:31], v[132:135], v[208:211], v[28:31]
	v_mfma_f32_16x16x32_bf16 v[24:27], v[140:143], v[208:211], v[24:27]
	v_mfma_f32_16x16x32_bf16 v[12:15], v[132:135], v[216:219], v[12:15]
	v_mfma_f32_16x16x32_bf16 v[8:11], v[140:143], v[216:219], v[8:11]
	v_mfma_f32_16x16x32_bf16 v[52:55], v[166:169], v[188:191], v[52:55]
	v_mfma_f32_16x16x32_bf16 v[48:51], v[180:183], v[188:191], v[48:51]
	v_mfma_f32_16x16x32_bf16 v[36:39], v[166:169], v[196:199], v[36:39]
	v_mfma_f32_16x16x32_bf16 v[32:35], v[180:183], v[196:199], v[32:35]
	v_mfma_f32_16x16x32_bf16 v[20:23], v[166:169], v[204:207], v[20:23]
	v_mfma_f32_16x16x32_bf16 v[16:19], v[180:183], v[204:207], v[16:19]
	v_mfma_f32_16x16x32_bf16 v[4:7], v[166:169], v[212:215], v[4:7]
	v_mfma_f32_16x16x32_bf16 v[0:3], v[180:183], v[212:215], v[0:3]
	v_mfma_f32_16x16x32_bf16 v[52:55], v[176:179], v[192:195], v[52:55]
	v_mfma_f32_16x16x32_bf16 v[48:51], v[184:187], v[192:195], v[48:51]
	v_mfma_f32_16x16x32_bf16 v[36:39], v[176:179], v[200:203], v[36:39]
	v_mfma_f32_16x16x32_bf16 v[32:35], v[184:187], v[200:203], v[32:35]
	v_mfma_f32_16x16x32_bf16 v[20:23], v[176:179], v[208:211], v[20:23]
	v_mfma_f32_16x16x32_bf16 v[16:19], v[184:187], v[208:211], v[16:19]
	v_mfma_f32_16x16x32_bf16 v[4:7], v[176:179], v[216:219], v[4:7]
	v_mfma_f32_16x16x32_bf16 v[0:3], v[184:187], v[216:219], v[0:3]
	s_setprio 0
	s_barrier
	s_add_u32 s0, s0, 0x100
	s_addc_u32 s1, s1, 0
	s_add_u32 s11, s11, 0x100
	s_addc_u32 s24, s24, 0
	s_cmp_ge_u32 s90, s60
	s_mov_b32 s2, s90
	s_cbranch_scc0 .LBB0_295
	s_branch .LBB0_297
